# GLA step A: log-rate load issued with the k/v pieces and unpacked under them (was load, vmcnt(0), unpack before the others)
# baseline (speedup 1.0000x reference)
.LBB0_454:
	s_lshl_b32 s10, s12, 4
	s_lshl_b32 s13, s12, 6
	s_and_b32 s10, s10, 0xfffff000
	s_and_b32 s13, s13, 0xfc0
	s_or_b32 s13, s10, s13
	s_waitcnt vmcnt(0)
	s_barrier
	s_and_saveexec_b64 s[14:15], s[0:1]
	s_cbranch_execz .LBB0_456
	v_or_b32_e32 v4, s13, v48
	v_mov_b64_e32 v[2:3], s[8:9]
	v_mad_i64_i32 v[2:3], s[16:17], v4, s22, v[2:3]
	v_mov_b32_e32 v23, v11
	v_lshl_add_u64 v[2:3], v[2:3], 0, v[22:23]
	v_add_co_u32_e32 v2, vcc, 0xc000, v2
	s_nop 1
	v_addc_co_u32_e32 v3, vcc, 0, v3, vcc
	global_load_dwordx4 v[124:127], v[2:3], off offset:2560

.LBB0_457:
	v_mov_b64_e32 v[120:121], s[8:9]
	v_and_b32_e32 v10, 0xf8, v25
	v_mad_i64_i32 v[120:121], s[16:17], v23, s22, v[120:121]
	v_lshlrev_b32_e32 v10, 1, v10
	v_lshl_add_u64 v[120:121], v[120:121], 0, s[10:11]
	v_lshl_add_u64 v[120:121], v[120:121], 0, v[10:11]
	v_add_co_u32_e32 v120, vcc, 0x1000, v120
	v_add_u32_e32 v25, 0x1000, v25
	s_nop 0
	v_addc_co_u32_e32 v121, vcc, 0, v121, vcc
	global_load_dwordx4 v[104:107], v[120:121], off offset:2048
	v_add_u32_e32 v23, 16, v23
	v_mov_b64_e32 v[120:121], s[8:9]
	v_and_b32_e32 v10, 0xf8, v25
	v_mad_i64_i32 v[120:121], s[16:17], v23, s22, v[120:121]
	v_lshlrev_b32_e32 v10, 1, v10
	v_lshl_add_u64 v[120:121], v[120:121], 0, s[10:11]
	v_lshl_add_u64 v[120:121], v[120:121], 0, v[10:11]
	v_add_co_u32_e32 v120, vcc, 0x1000, v120
	v_add_u32_e32 v25, 0x1000, v25
	s_nop 0
	v_addc_co_u32_e32 v121, vcc, 0, v121, vcc
	global_load_dwordx4 v[108:111], v[120:121], off offset:2048
	v_add_u32_e32 v23, 16, v23
	v_mov_b64_e32 v[120:121], s[8:9]
	v_and_b32_e32 v10, 0xf8, v25
	v_mad_i64_i32 v[120:121], s[16:17], v23, s22, v[120:121]
	v_lshlrev_b32_e32 v10, 1, v10
	v_lshl_add_u64 v[120:121], v[120:121], 0, s[10:11]
	v_lshl_add_u64 v[120:121], v[120:121], 0, v[10:11]
	v_add_co_u32_e32 v120, vcc, 0x1000, v120
	v_add_u32_e32 v25, 0x1000, v25
	s_nop 0
	v_addc_co_u32_e32 v121, vcc, 0, v121, vcc
	global_load_dwordx4 v[112:115], v[120:121], off offset:2048
	v_add_u32_e32 v23, 16, v23
	v_mov_b64_e32 v[120:121], s[8:9]
	v_and_b32_e32 v10, 0xf8, v25
	v_mad_i64_i32 v[120:121], s[16:17], v23, s22, v[120:121]
	v_lshlrev_b32_e32 v10, 1, v10
	v_lshl_add_u64 v[120:121], v[120:121], 0, s[10:11]
	v_lshl_add_u64 v[120:121], v[120:121], 0, v[10:11]
	v_add_co_u32_e32 v120, vcc, 0x1000, v120
	v_add_u32_e32 v25, 0x1000, v25
	s_nop 0
	v_addc_co_u32_e32 v121, vcc, 0, v121, vcc
	global_load_dwordx4 v[116:119], v[120:121], off offset:2048
	v_add_u32_e32 v23, 16, v23
	s_and_saveexec_b64 vcc, s[0:1]
	s_waitcnt vmcnt(6)
	v_lshlrev_b32_e32 v128, 16, v124
	v_and_b32_e32 v129, 0xffff0000, v124
	v_lshlrev_b32_e32 v130, 16, v125
	v_and_b32_e32 v131, 0xffff0000, v125
	v_lshlrev_b32_e32 v132, 16, v126
	v_and_b32_e32 v133, 0xffff0000, v126
	v_lshlrev_b32_e32 v134, 16, v127
	v_and_b32_e32 v135, 0xffff0000, v127
	ds_write_b128 v50, v[128:131]
	ds_write_b128 v50, v[132:135] offset:16
	s_mov_b64 exec, vcc
	s_waitcnt vmcnt(3)
	ds_write_b128 v27, v[104:107]
	v_add_u32_e32 v27, 0x2100, v27
	s_waitcnt vmcnt(2)
	ds_write_b128 v27, v[108:111]
	v_add_u32_e32 v27, 0x2100, v27
	s_waitcnt vmcnt(1)
	ds_write_b128 v27, v[112:115]
	v_add_u32_e32 v27, 0x2100, v27
	s_waitcnt vmcnt(0)
	ds_write_b128 v27, v[116:119]
	v_add_u32_e32 v27, 0x2100, v27
	s_or_b64 exec, exec, s[14:15]
	v_or_b32_e32 v10, s30, v29
	v_readlane_b32 s36, v249, 0
	v_lshlrev_b32_e32 v10, 2, v10
	v_readlane_b32 s48, v249, 12
	v_readlane_b32 s49, v249, 13
	s_waitcnt lgkmcnt(0)
	s_barrier
	v_lshl_add_u64 v[108:109], s[48:49], 0, v[10:11]
	v_add_co_u32_e32 v96, vcc, 0x1000, v108
	s_nop 1
	v_addc_co_u32_e32 v97, vcc, 0, v109, vcc
	v_add_co_u32_e32 v98, vcc, 0x2000, v108
	v_readlane_b32 s50, v249, 14
	s_nop 0
	v_addc_co_u32_e32 v99, vcc, 0, v109, vcc
	v_add_co_u32_e32 v102, vcc, 0x3000, v108
	v_readlane_b32 s51, v249, 15
	s_nop 0
	v_addc_co_u32_e32 v103, vcc, 0, v109, vcc
	v_add_co_u32_e32 v110, vcc, 0x4000, v108
	v_readlane_b32 s37, v249, 1
	s_nop 0
	v_addc_co_u32_e32 v111, vcc, 0, v109, vcc
	global_load_dword v26, v10, s[48:49]
	global_load_dword v25, v10, s[48:49] offset:2048
	global_load_dword v23, v10, s[50:51]
	global_load_dword v107, v[96:97], off
	global_load_dword v106, v[96:97], off offset:2048
	global_load_dword v104, v[98:99], off
	global_load_dword v101, v[98:99], off offset:2048
	s_nop 0
	global_load_dword v98, v[102:103], off
	global_load_dword v96, v[102:103], off offset:2048
	global_load_dword v95, v[110:111], off
	global_load_dword v27, v[110:111], off offset:2048
	v_add_co_u32_e32 v102, vcc, 0x5000, v108
	v_mov_b32_e32 v10, 0
	s_nop 0
	v_addc_co_u32_e32 v103, vcc, 0, v109, vcc
	v_add_co_u32_e32 v110, vcc, 0x6000, v108
	v_readlane_b32 s38, v249, 2
	s_nop 0
	v_addc_co_u32_e32 v111, vcc, 0, v109, vcc
	global_load_dword v105, v[102:103], off
	s_nop 0
	global_load_dword v102, v[102:103], off offset:2048
	s_nop 0
	global_load_dword v99, v[110:111], off
	global_load_dword v97, v[110:111], off offset:2048
	v_add_co_u32_e32 v108, vcc, 0x7000, v108
	v_readlane_b32 s39, v249, 3
	s_nop 0
	v_addc_co_u32_e32 v109, vcc, 0, v109, vcc
	global_load_dword v103, v[108:109], off
	global_load_dword v100, v[108:109], off offset:2048
	ds_read_b128 v[108:111], v55
	ds_read_b128 v[112:115], v55 offset:16
	ds_read_b128 v[116:119], v55 offset:32
	ds_read_b128 v[120:123], v55 offset:48
	ds_read_b128 v[124:127], v56
	ds_read_b128 v[128:131], v56 offset:16
	ds_read_b128 v[132:135], v56 offset:32
	ds_read_b128 v[136:139], v56 offset:48
	ds_read_b128 v[140:143], v57
	v_readlane_b32 s40, v249, 4
	v_readlane_b32 s41, v249, 5
	v_readlane_b32 s42, v249, 6
	v_readlane_b32 s43, v249, 7
	v_readlane_b32 s44, v249, 8
	v_readlane_b32 s45, v249, 9
	v_readlane_b32 s46, v249, 10
	v_readlane_b32 s47, v249, 11
	s_waitcnt vmcnt(14) lgkmcnt(8)
	v_fma_f32 v108, v26, v108, v23
	v_fmac_f32_e32 v108, v25, v109
	s_waitcnt vmcnt(13)
	v_fmac_f32_e32 v108, v107, v110
	s_waitcnt vmcnt(12)
	v_fmac_f32_e32 v108, v106, v111
	s_waitcnt vmcnt(11) lgkmcnt(7)
	v_fmac_f32_e32 v108, v104, v112
	s_waitcnt vmcnt(10)
	v_fmac_f32_e32 v108, v101, v113
	s_waitcnt vmcnt(9)
	v_fmac_f32_e32 v108, v98, v114
	s_waitcnt lgkmcnt(4)
	v_fma_f32 v124, v26, v124, v23
	s_waitcnt vmcnt(8)
	v_fmac_f32_e32 v108, v96, v115
	v_fmac_f32_e32 v124, v25, v125
	s_waitcnt vmcnt(7)
	v_fmac_f32_e32 v108, v95, v116
	v_fmac_f32_e32 v124, v107, v126
	s_waitcnt vmcnt(6)
	v_fmac_f32_e32 v108, v27, v117
	v_fmac_f32_e32 v124, v106, v127
	s_waitcnt lgkmcnt(3)
	v_fmac_f32_e32 v124, v104, v128
	v_fmac_f32_e32 v124, v101, v129
	s_waitcnt vmcnt(5)
	v_fmac_f32_e32 v108, v105, v118
	s_waitcnt vmcnt(4)
	v_fmac_f32_e32 v108, v102, v119
	s_waitcnt vmcnt(3)
	v_fmac_f32_e32 v108, v99, v120
	v_fmac_f32_e32 v124, v98, v130
	s_waitcnt vmcnt(2)
	v_fmac_f32_e32 v108, v97, v121
	v_fmac_f32_e32 v124, v96, v131
	s_waitcnt lgkmcnt(2)
	v_fmac_f32_e32 v124, v95, v132
	v_fmac_f32_e32 v124, v27, v133
	s_waitcnt vmcnt(1)
	v_fmac_f32_e32 v108, v103, v122
	s_waitcnt vmcnt(0)
	v_fmac_f32_e32 v108, v100, v123
	v_mul_f32_e64 v109, |v108|, s25
	v_fmac_f32_e32 v124, v105, v134
	v_exp_f32_e32 v109, v109
	v_fmac_f32_e32 v124, v102, v135
	s_waitcnt lgkmcnt(1)
	v_fmac_f32_e32 v124, v99, v136
	v_fmac_f32_e32 v124, v97, v137
	v_fmac_f32_e32 v124, v103, v138
	v_add_f32_e32 v109, 1.0, v109
	v_fmac_f32_e32 v124, v100, v139
	v_log_f32_e32 v109, v109
	v_mul_f32_e64 v110, |v124|, s25
	v_exp_f32_e32 v110, v110
	v_min_f32_e32 v108, 0, v108
	v_fmac_f32_e32 v108, 0xbf317218, v109
	v_fma_f32 v108, v108, s26, 0
	v_add_f32_e32 v110, 1.0, v110
	ds_write_b32 v78, v108 offset:4096
	s_waitcnt lgkmcnt(1)
	v_fma_f32 v109, v26, v140, v23
	v_log_f32_e32 v122, v110
	ds_read_b128 v[110:113], v57 offset:16
	ds_read_b128 v[114:117], v57 offset:32
	ds_read_b128 v[118:121], v57 offset:48
	v_fmac_f32_e32 v109, v25, v141
	v_fmac_f32_e32 v109, v107, v142
	v_fmac_f32_e32 v109, v106, v143
	s_waitcnt lgkmcnt(2)
	v_fmac_f32_e32 v109, v104, v110
	v_fmac_f32_e32 v109, v101, v111
	v_fmac_f32_e32 v109, v98, v112
	v_fmac_f32_e32 v109, v96, v113
	s_waitcnt lgkmcnt(1)
	v_fmac_f32_e32 v109, v95, v114
	v_fmac_f32_e32 v109, v27, v115
	v_fmac_f32_e32 v109, v105, v116
	v_fmac_f32_e32 v109, v102, v117
	s_waitcnt lgkmcnt(0)
	v_fmac_f32_e32 v109, v99, v118
	v_fmac_f32_e32 v109, v97, v119
	v_fmac_f32_e32 v109, v103, v120
	v_fmac_f32_e32 v109, v100, v121
	v_mul_f32_e64 v110, |v109|, s25
	v_exp_f32_e32 v110, v110
	v_min_f32_e32 v111, 0, v124
	v_fmac_f32_e32 v111, 0xbf317218, v122
	v_fmac_f32_e32 v108, 0x3d800000, v111
	v_add_f32_e32 v110, 1.0, v110
	v_log_f32_e32 v114, v110
	ds_read_b128 v[110:113], v58
	ds_write_b32 v79, v108 offset:4096
	v_min_f32_e32 v109, 0, v109
	v_fmac_f32_e32 v109, 0xbf317218, v114
	ds_read_b128 v[114:117], v58 offset:16
	ds_read_b128 v[118:121], v58 offset:32
	ds_read_b128 v[122:125], v58 offset:48
	s_waitcnt lgkmcnt(4)
	v_fma_f32 v110, v26, v110, v23
	v_fmac_f32_e32 v110, v25, v111
	v_fmac_f32_e32 v110, v107, v112
	v_fmac_f32_e32 v110, v106, v113
	s_waitcnt lgkmcnt(2)
	v_fmac_f32_e32 v110, v104, v114
	v_fmac_f32_e32 v110, v101, v115
	v_fmac_f32_e32 v110, v98, v116
	v_fmac_f32_e32 v110, v96, v117
	s_waitcnt lgkmcnt(1)
	v_fmac_f32_e32 v110, v95, v118
	v_fmac_f32_e32 v110, v27, v119
	v_fmac_f32_e32 v110, v105, v120
	v_fmac_f32_e32 v110, v102, v121
	s_waitcnt lgkmcnt(0)
	v_fmac_f32_e32 v110, v99, v122
	v_fmac_f32_e32 v110, v97, v123
	v_fmac_f32_e32 v110, v103, v124
	v_fmac_f32_e32 v110, v100, v125
	v_mul_f32_e64 v111, |v110|, s25
	v_exp_f32_e32 v111, v111
	v_fmac_f32_e32 v108, 0x3d800000, v109
	v_min_f32_e32 v109, 0, v110
	ds_write_b32 v80, v108 offset:4096
	v_add_f32_e32 v114, 1.0, v111
	ds_read_b128 v[110:113], v59
	v_log_f32_e32 v126, v114
	ds_read_b128 v[114:117], v59 offset:16
	ds_read_b128 v[118:121], v59 offset:32
	ds_read_b128 v[122:125], v59 offset:48
	s_waitcnt lgkmcnt(3)
	v_fma_f32 v127, v26, v110, v23
	v_fmac_f32_e32 v127, v25, v111
	v_fmac_f32_e32 v127, v107, v112
	v_fmac_f32_e32 v127, v106, v113
	s_waitcnt lgkmcnt(2)
	v_fmac_f32_e32 v127, v104, v114
	v_fmac_f32_e32 v127, v101, v115
	v_fmac_f32_e32 v127, v98, v116
	v_fmac_f32_e32 v127, v96, v117
	s_waitcnt lgkmcnt(1)
	v_fmac_f32_e32 v127, v95, v118
	v_fmac_f32_e32 v127, v27, v119
	v_fmac_f32_e32 v127, v105, v120
	v_fmac_f32_e32 v127, v102, v121
	s_waitcnt lgkmcnt(0)
	v_fmac_f32_e32 v127, v99, v122
	v_fmac_f32_e32 v127, v97, v123
	v_fmac_f32_e32 v127, v103, v124
	v_fmac_f32_e32 v127, v100, v125
	v_mul_f32_e64 v110, |v127|, s25
	v_exp_f32_e32 v110, v110
	v_fmac_f32_e32 v109, 0xbf317218, v126
	v_fmac_f32_e32 v108, 0x3d800000, v109
	ds_write_b32 v81, v108 offset:4096
	v_add_f32_e32 v109, 1.0, v110
	ds_read_b128 v[110:113], v60
	ds_read_b128 v[114:117], v60 offset:16
	ds_read_b128 v[118:121], v60 offset:32
	ds_read_b128 v[122:125], v60 offset:48
	v_log_f32_e32 v109, v109
	s_waitcnt lgkmcnt(3)
	v_fma_f32 v110, v26, v110, v23
	v_fmac_f32_e32 v110, v25, v111
	v_fmac_f32_e32 v110, v107, v112
	v_fmac_f32_e32 v110, v106, v113
	s_waitcnt lgkmcnt(2)
	v_fmac_f32_e32 v110, v104, v114
	v_fmac_f32_e32 v110, v101, v115
	v_fmac_f32_e32 v110, v98, v116
	v_fmac_f32_e32 v110, v96, v117
	s_waitcnt lgkmcnt(1)
	v_fmac_f32_e32 v110, v95, v118
	v_fmac_f32_e32 v110, v27, v119
	v_fmac_f32_e32 v110, v105, v120
	v_fmac_f32_e32 v110, v102, v121
	s_waitcnt lgkmcnt(0)
	v_fmac_f32_e32 v110, v99, v122
	v_fmac_f32_e32 v110, v97, v123
	v_fmac_f32_e32 v110, v103, v124
	v_fmac_f32_e32 v110, v100, v125
	v_mul_f32_e64 v111, |v110|, s25
	v_exp_f32_e32 v111, v111
	v_min_f32_e32 v112, 0, v127
	v_fmac_f32_e32 v112, 0xbf317218, v109
	v_fmac_f32_e32 v108, 0x3d800000, v112
	v_add_f32_e32 v109, 1.0, v111
	v_min_f32_e32 v126, 0, v110
	ds_read_b128 v[110:113], v61
	v_log_f32_e32 v109, v109
	ds_write_b32 v82, v108 offset:4096
	ds_read_b128 v[114:117], v61 offset:16
	ds_read_b128 v[118:121], v61 offset:32
	ds_read_b128 v[122:125], v61 offset:48
	v_fmac_f32_e32 v126, 0xbf317218, v109
	s_waitcnt lgkmcnt(4)
	v_fma_f32 v109, v26, v110, v23
	v_fmac_f32_e32 v109, v25, v111
	v_fmac_f32_e32 v109, v107, v112
	v_fmac_f32_e32 v109, v106, v113
	s_waitcnt lgkmcnt(2)
	v_fmac_f32_e32 v109, v104, v114
	v_fmac_f32_e32 v109, v101, v115
	v_fmac_f32_e32 v109, v98, v116
	v_fmac_f32_e32 v109, v96, v117
	s_waitcnt lgkmcnt(1)
	v_fmac_f32_e32 v109, v95, v118
	v_fmac_f32_e32 v109, v27, v119
	v_fmac_f32_e32 v109, v105, v120
	v_fmac_f32_e32 v109, v102, v121
	s_waitcnt lgkmcnt(0)
	v_fmac_f32_e32 v109, v99, v122
	v_fmac_f32_e32 v109, v97, v123
	v_fmac_f32_e32 v109, v103, v124
	v_fmac_f32_e32 v109, v100, v125
	v_mul_f32_e64 v110, |v109|, s25
	v_exp_f32_e32 v110, v110
	v_fmac_f32_e32 v108, 0x3d800000, v126
	ds_write_b32 v83, v108 offset:4096
	v_min_f32_e32 v109, 0, v109
	v_add_f32_e32 v114, 1.0, v110
	ds_read_b128 v[110:113], v62
	v_log_f32_e32 v126, v114
	ds_read_b128 v[114:117], v62 offset:16
	ds_read_b128 v[118:121], v62 offset:32
	ds_read_b128 v[122:125], v62 offset:48
	s_waitcnt lgkmcnt(3)
	v_fma_f32 v127, v26, v110, v23
	v_fmac_f32_e32 v127, v25, v111
	v_fmac_f32_e32 v127, v107, v112
	v_fmac_f32_e32 v127, v106, v113
	s_waitcnt lgkmcnt(2)
	v_fmac_f32_e32 v127, v104, v114
	v_fmac_f32_e32 v127, v101, v115
	v_fmac_f32_e32 v127, v98, v116
	v_fmac_f32_e32 v127, v96, v117
	s_waitcnt lgkmcnt(1)
	v_fmac_f32_e32 v127, v95, v118
	v_fmac_f32_e32 v127, v27, v119
	v_fmac_f32_e32 v127, v105, v120
	v_fmac_f32_e32 v127, v102, v121
	s_waitcnt lgkmcnt(0)
	v_fmac_f32_e32 v127, v99, v122
	v_fmac_f32_e32 v127, v97, v123
	v_fmac_f32_e32 v127, v103, v124
	v_fmac_f32_e32 v127, v100, v125
	v_mul_f32_e64 v110, |v127|, s25
	v_exp_f32_e32 v110, v110
	v_fmac_f32_e32 v109, 0xbf317218, v126
	v_fmac_f32_e32 v108, 0x3d800000, v109
	ds_write_b32 v84, v108 offset:4096
	v_add_f32_e32 v109, 1.0, v110
	ds_read_b128 v[110:113], v63
	ds_read_b128 v[114:117], v63 offset:16
	ds_read_b128 v[118:121], v63 offset:32
	ds_read_b128 v[122:125], v63 offset:48
	v_log_f32_e32 v109, v109
	s_waitcnt lgkmcnt(3)
	v_fma_f32 v110, v26, v110, v23
	v_fmac_f32_e32 v110, v25, v111
	v_fmac_f32_e32 v110, v107, v112
	v_fmac_f32_e32 v110, v106, v113
	s_waitcnt lgkmcnt(2)
	v_fmac_f32_e32 v110, v104, v114
	v_fmac_f32_e32 v110, v101, v115
	v_fmac_f32_e32 v110, v98, v116
	v_fmac_f32_e32 v110, v96, v117
	s_waitcnt lgkmcnt(1)
	v_fmac_f32_e32 v110, v95, v118
	v_fmac_f32_e32 v110, v27, v119
	v_fmac_f32_e32 v110, v105, v120
	v_fmac_f32_e32 v110, v102, v121
	s_waitcnt lgkmcnt(0)
	v_fmac_f32_e32 v110, v99, v122
	v_fmac_f32_e32 v110, v97, v123
	v_fmac_f32_e32 v110, v103, v124
	v_fmac_f32_e32 v110, v100, v125
	v_mul_f32_e64 v111, |v110|, s25
	v_exp_f32_e32 v111, v111
	v_min_f32_e32 v112, 0, v127
	v_fmac_f32_e32 v112, 0xbf317218, v109
	v_fmac_f32_e32 v108, 0x3d800000, v112
	v_add_f32_e32 v109, 1.0, v111
	v_min_f32_e32 v126, 0, v110
	ds_read_b128 v[110:113], v64
	v_log_f32_e32 v109, v109
	ds_write_b32 v85, v108 offset:4096
	ds_read_b128 v[114:117], v64 offset:16
	ds_read_b128 v[118:121], v64 offset:32
	ds_read_b128 v[122:125], v64 offset:48
	v_fmac_f32_e32 v126, 0xbf317218, v109
	s_waitcnt lgkmcnt(4)
	v_fma_f32 v109, v26, v110, v23
	v_fmac_f32_e32 v109, v25, v111
	v_fmac_f32_e32 v109, v107, v112
	v_fmac_f32_e32 v109, v106, v113
	s_waitcnt lgkmcnt(2)
	v_fmac_f32_e32 v109, v104, v114
	v_fmac_f32_e32 v109, v101, v115
	v_fmac_f32_e32 v109, v98, v116
	v_fmac_f32_e32 v109, v96, v117
	s_waitcnt lgkmcnt(1)
	v_fmac_f32_e32 v109, v95, v118
	v_fmac_f32_e32 v109, v27, v119
	v_fmac_f32_e32 v109, v105, v120
	v_fmac_f32_e32 v109, v102, v121
	s_waitcnt lgkmcnt(0)
	v_fmac_f32_e32 v109, v99, v122
	v_fmac_f32_e32 v109, v97, v123
	v_fmac_f32_e32 v109, v103, v124
	v_fmac_f32_e32 v109, v100, v125
	v_mul_f32_e64 v110, |v109|, s25
	v_exp_f32_e32 v110, v110
	v_fmac_f32_e32 v108, 0x3d800000, v126
	ds_write_b32 v86, v108 offset:4096
	v_min_f32_e32 v109, 0, v109
	v_add_f32_e32 v114, 1.0, v110
	ds_read_b128 v[110:113], v65
	v_log_f32_e32 v126, v114
	ds_read_b128 v[114:117], v65 offset:16
	ds_read_b128 v[118:121], v65 offset:32
	ds_read_b128 v[122:125], v65 offset:48
	s_waitcnt lgkmcnt(3)
	v_fma_f32 v127, v26, v110, v23
	v_fmac_f32_e32 v127, v25, v111
	v_fmac_f32_e32 v127, v107, v112
	v_fmac_f32_e32 v127, v106, v113
	s_waitcnt lgkmcnt(2)
	v_fmac_f32_e32 v127, v104, v114
	v_fmac_f32_e32 v127, v101, v115
	v_fmac_f32_e32 v127, v98, v116
	v_fmac_f32_e32 v127, v96, v117
	s_waitcnt lgkmcnt(1)
	v_fmac_f32_e32 v127, v95, v118
	v_fmac_f32_e32 v127, v27, v119
	v_fmac_f32_e32 v127, v105, v120
	v_fmac_f32_e32 v127, v102, v121
	s_waitcnt lgkmcnt(0)
	v_fmac_f32_e32 v127, v99, v122
	v_fmac_f32_e32 v127, v97, v123
	v_fmac_f32_e32 v127, v103, v124
	v_fmac_f32_e32 v127, v100, v125
	v_mul_f32_e64 v110, |v127|, s25
	v_exp_f32_e32 v110, v110
	v_fmac_f32_e32 v109, 0xbf317218, v126
	v_fmac_f32_e32 v108, 0x3d800000, v109
	ds_write_b32 v87, v108 offset:4096
	v_add_f32_e32 v109, 1.0, v110
	ds_read_b128 v[110:113], v66
	ds_read_b128 v[114:117], v66 offset:16
	ds_read_b128 v[118:121], v66 offset:32
	ds_read_b128 v[122:125], v66 offset:48
	v_log_f32_e32 v109, v109
	s_waitcnt lgkmcnt(3)
	v_fma_f32 v110, v26, v110, v23
	v_fmac_f32_e32 v110, v25, v111
	v_fmac_f32_e32 v110, v107, v112
	v_fmac_f32_e32 v110, v106, v113
	s_waitcnt lgkmcnt(2)
	v_fmac_f32_e32 v110, v104, v114
	v_fmac_f32_e32 v110, v101, v115
	v_fmac_f32_e32 v110, v98, v116
	v_fmac_f32_e32 v110, v96, v117
	s_waitcnt lgkmcnt(1)
	v_fmac_f32_e32 v110, v95, v118
	v_fmac_f32_e32 v110, v27, v119
	v_fmac_f32_e32 v110, v105, v120
	v_fmac_f32_e32 v110, v102, v121
	s_waitcnt lgkmcnt(0)
	v_fmac_f32_e32 v110, v99, v122
	v_fmac_f32_e32 v110, v97, v123
	v_fmac_f32_e32 v110, v103, v124
	v_fmac_f32_e32 v110, v100, v125
	v_mul_f32_e64 v111, |v110|, s25
	v_exp_f32_e32 v111, v111
	v_min_f32_e32 v112, 0, v127
	v_fmac_f32_e32 v112, 0xbf317218, v109
	v_fmac_f32_e32 v108, 0x3d800000, v112
	v_add_f32_e32 v109, 1.0, v111
	v_min_f32_e32 v126, 0, v110
	ds_read_b128 v[110:113], v67
	v_log_f32_e32 v109, v109
	ds_write_b32 v88, v108 offset:4096
	ds_read_b128 v[114:117], v67 offset:16
	ds_read_b128 v[118:121], v67 offset:32
	ds_read_b128 v[122:125], v67 offset:48
	v_fmac_f32_e32 v126, 0xbf317218, v109
	s_waitcnt lgkmcnt(4)
	v_fma_f32 v109, v26, v110, v23
	v_fmac_f32_e32 v109, v25, v111
	v_fmac_f32_e32 v109, v107, v112
	v_fmac_f32_e32 v109, v106, v113
	s_waitcnt lgkmcnt(2)
	v_fmac_f32_e32 v109, v104, v114
	v_fmac_f32_e32 v109, v101, v115
	v_fmac_f32_e32 v109, v98, v116
	v_fmac_f32_e32 v109, v96, v117
	s_waitcnt lgkmcnt(1)
	v_fmac_f32_e32 v109, v95, v118
	v_fmac_f32_e32 v109, v27, v119
	v_fmac_f32_e32 v109, v105, v120
	v_fmac_f32_e32 v109, v102, v121
	s_waitcnt lgkmcnt(0)
	v_fmac_f32_e32 v109, v99, v122
	v_fmac_f32_e32 v109, v97, v123
	v_fmac_f32_e32 v109, v103, v124
	v_fmac_f32_e32 v109, v100, v125
	v_mul_f32_e64 v110, |v109|, s25
	v_exp_f32_e32 v110, v110
	v_fmac_f32_e32 v108, 0x3d800000, v126
	ds_write_b32 v89, v108 offset:4096
	v_min_f32_e32 v109, 0, v109
	v_add_f32_e32 v114, 1.0, v110
	ds_read_b128 v[110:113], v68
	v_log_f32_e32 v126, v114
	ds_read_b128 v[114:117], v68 offset:16
	ds_read_b128 v[118:121], v68 offset:32
	ds_read_b128 v[122:125], v68 offset:48
	s_waitcnt lgkmcnt(3)
	v_fma_f32 v127, v26, v110, v23
	v_fmac_f32_e32 v127, v25, v111
	v_fmac_f32_e32 v127, v107, v112
	v_fmac_f32_e32 v127, v106, v113
	s_waitcnt lgkmcnt(2)
	v_fmac_f32_e32 v127, v104, v114
	v_fmac_f32_e32 v127, v101, v115
	v_fmac_f32_e32 v127, v98, v116
	v_fmac_f32_e32 v127, v96, v117
	s_waitcnt lgkmcnt(1)
	v_fmac_f32_e32 v127, v95, v118
	v_fmac_f32_e32 v127, v27, v119
	v_fmac_f32_e32 v127, v105, v120
	v_fmac_f32_e32 v127, v102, v121
	s_waitcnt lgkmcnt(0)
	v_fmac_f32_e32 v127, v99, v122
	v_fmac_f32_e32 v127, v97, v123
	v_fmac_f32_e32 v127, v103, v124
	v_fmac_f32_e32 v127, v100, v125
	v_mul_f32_e64 v110, |v127|, s25
	v_exp_f32_e32 v110, v110
	v_fmac_f32_e32 v109, 0xbf317218, v126
	v_fmac_f32_e32 v108, 0x3d800000, v109
	ds_write_b32 v90, v108 offset:4096
	v_add_f32_e32 v109, 1.0, v110
	ds_read_b128 v[110:113], v69
	ds_read_b128 v[114:117], v69 offset:16
	ds_read_b128 v[118:121], v69 offset:32
	ds_read_b128 v[122:125], v69 offset:48
	v_log_f32_e32 v109, v109
	s_waitcnt lgkmcnt(3)
	v_fma_f32 v126, v26, v110, v23
	v_fmac_f32_e32 v126, v25, v111
	v_fmac_f32_e32 v126, v107, v112
	v_fmac_f32_e32 v126, v106, v113
	s_waitcnt lgkmcnt(2)
	v_fmac_f32_e32 v126, v104, v114
	v_fmac_f32_e32 v126, v101, v115
	v_fmac_f32_e32 v126, v98, v116
	v_fmac_f32_e32 v126, v96, v117
	s_waitcnt lgkmcnt(1)
	v_fmac_f32_e32 v126, v95, v118
	v_fmac_f32_e32 v126, v27, v119
	v_fmac_f32_e32 v126, v105, v120
	v_fmac_f32_e32 v126, v102, v121
	s_waitcnt lgkmcnt(0)
	v_fmac_f32_e32 v126, v99, v122
	v_fmac_f32_e32 v126, v97, v123
	v_fmac_f32_e32 v126, v103, v124
	v_fmac_f32_e32 v126, v100, v125
	v_mul_f32_e64 v110, |v126|, s25
	v_exp_f32_e32 v110, v110
	v_min_f32_e32 v111, 0, v127
	v_fmac_f32_e32 v111, 0xbf317218, v109
	v_fmac_f32_e32 v108, 0x3d800000, v111
	v_add_f32_e32 v109, 1.0, v110
	ds_read_b128 v[110:113], v70
	ds_read_b128 v[114:117], v70 offset:16
	ds_read_b128 v[118:121], v70 offset:32
	ds_read_b128 v[122:125], v70 offset:48
	v_log_f32_e32 v109, v109
	ds_write_b32 v91, v108 offset:4096
	s_waitcnt lgkmcnt(4)
	v_fmac_f32_e32 v23, v26, v110
	v_fmac_f32_e32 v23, v25, v111
	v_fmac_f32_e32 v23, v107, v112
	v_fmac_f32_e32 v23, v106, v113
	s_waitcnt lgkmcnt(3)
	v_fmac_f32_e32 v23, v104, v114
	v_fmac_f32_e32 v23, v101, v115
	v_fmac_f32_e32 v23, v98, v116
	v_fmac_f32_e32 v23, v96, v117
	s_waitcnt lgkmcnt(2)
	v_fmac_f32_e32 v23, v95, v118
	v_fmac_f32_e32 v23, v27, v119
	v_fmac_f32_e32 v23, v105, v120
	v_fmac_f32_e32 v23, v102, v121
	s_waitcnt lgkmcnt(1)
	v_fmac_f32_e32 v23, v99, v122
	v_fmac_f32_e32 v23, v97, v123
	v_fmac_f32_e32 v23, v103, v124
	v_fmac_f32_e32 v23, v100, v125
	v_mul_f32_e64 v25, |v23|, s25
	v_exp_f32_e32 v25, v25
	v_min_f32_e32 v26, 0, v126
	v_fmac_f32_e32 v26, 0xbf317218, v109
	v_min_f32_e32 v23, 0, v23
	v_add_f32_e32 v25, 1.0, v25
	v_log_f32_e32 v25, v25
	v_fmac_f32_e32 v108, 0x3d800000, v26
	ds_write_b32 v92, v108 offset:4096
	v_fmac_f32_e32 v23, 0xbf317218, v25
	v_fmac_f32_e32 v108, 0x3d800000, v23
	ds_write_b32 v93, v108 offset:4096
	ds_write_b32 v192, v108 offset:36864
	s_waitcnt lgkmcnt(0)
	s_barrier
	s_and_saveexec_b64 s[14:15], s[4:5]
	s_cbranch_execz .LBB0_462
	v_mov_b32_e32 v10, 0
	s_mov_b64 s[16:17], 0
	v_mov_b32_e32 v23, v54
	v_mov_b32_e32 v25, v30

.LBB0_1237:
	s_lshl_b32 s10, s12, 4
	s_lshl_b32 s13, s12, 6
	s_and_b32 s10, s10, 0xfffff000
	s_and_b32 s13, s13, 0xfc0
	s_or_b32 s13, s10, s13
	s_waitcnt vmcnt(0)
	s_barrier
	s_and_saveexec_b64 s[14:15], s[4:5]
	s_cbranch_execz .LBB0_1239
	v_or_b32_e32 v4, s13, v47
	v_mov_b64_e32 v[2:3], s[2:3]
	v_mad_i64_i32 v[2:3], s[16:17], v4, s23, v[2:3]
	v_mov_b32_e32 v23, v11
	v_lshl_add_u64 v[2:3], v[2:3], 0, v[22:23]
	v_add_co_u32_e32 v2, vcc, 0xc000, v2
	s_nop 1
	v_addc_co_u32_e32 v3, vcc, 0, v3, vcc
	global_load_dwordx4 v[124:127], v[2:3], off offset:2560

.LBB0_1240:
	v_mov_b64_e32 v[120:121], s[2:3]
	v_and_b32_e32 v10, 0xf8, v25
	v_mad_i64_i32 v[120:121], s[16:17], v23, s23, v[120:121]
	v_lshlrev_b32_e32 v10, 1, v10
	v_lshl_add_u64 v[120:121], v[120:121], 0, s[10:11]
	v_lshl_add_u64 v[120:121], v[120:121], 0, v[10:11]
	v_add_co_u32_e32 v120, vcc, 0x1000, v120
	v_add_u32_e32 v25, 0x1000, v25
	s_nop 0
	v_addc_co_u32_e32 v121, vcc, 0, v121, vcc
	global_load_dwordx4 v[104:107], v[120:121], off offset:2048
	v_add_u32_e32 v23, 16, v23
	v_mov_b64_e32 v[120:121], s[2:3]
	v_and_b32_e32 v10, 0xf8, v25
	v_mad_i64_i32 v[120:121], s[16:17], v23, s23, v[120:121]
	v_lshlrev_b32_e32 v10, 1, v10
	v_lshl_add_u64 v[120:121], v[120:121], 0, s[10:11]
	v_lshl_add_u64 v[120:121], v[120:121], 0, v[10:11]
	v_add_co_u32_e32 v120, vcc, 0x1000, v120
	v_add_u32_e32 v25, 0x1000, v25
	s_nop 0
	v_addc_co_u32_e32 v121, vcc, 0, v121, vcc
	global_load_dwordx4 v[108:111], v[120:121], off offset:2048
	v_add_u32_e32 v23, 16, v23
	v_mov_b64_e32 v[120:121], s[2:3]
	v_and_b32_e32 v10, 0xf8, v25
	v_mad_i64_i32 v[120:121], s[16:17], v23, s23, v[120:121]
	v_lshlrev_b32_e32 v10, 1, v10
	v_lshl_add_u64 v[120:121], v[120:121], 0, s[10:11]
	v_lshl_add_u64 v[120:121], v[120:121], 0, v[10:11]
	v_add_co_u32_e32 v120, vcc, 0x1000, v120
	v_add_u32_e32 v25, 0x1000, v25
	s_nop 0
	v_addc_co_u32_e32 v121, vcc, 0, v121, vcc
	global_load_dwordx4 v[112:115], v[120:121], off offset:2048
	v_add_u32_e32 v23, 16, v23
	v_mov_b64_e32 v[120:121], s[2:3]
	v_and_b32_e32 v10, 0xf8, v25
	v_mad_i64_i32 v[120:121], s[16:17], v23, s23, v[120:121]
	v_lshlrev_b32_e32 v10, 1, v10
	v_lshl_add_u64 v[120:121], v[120:121], 0, s[10:11]
	v_lshl_add_u64 v[120:121], v[120:121], 0, v[10:11]
	v_add_co_u32_e32 v120, vcc, 0x1000, v120
	v_add_u32_e32 v25, 0x1000, v25
	s_nop 0
	v_addc_co_u32_e32 v121, vcc, 0, v121, vcc
	global_load_dwordx4 v[116:119], v[120:121], off offset:2048
	v_add_u32_e32 v23, 16, v23
	s_and_saveexec_b64 vcc, s[4:5]
	s_waitcnt vmcnt(6)
	v_lshlrev_b32_e32 v128, 16, v124
	v_and_b32_e32 v129, 0xffff0000, v124
	v_lshlrev_b32_e32 v130, 16, v125
	v_and_b32_e32 v131, 0xffff0000, v125
	v_lshlrev_b32_e32 v132, 16, v126
	v_and_b32_e32 v133, 0xffff0000, v126
	v_lshlrev_b32_e32 v134, 16, v127
	v_and_b32_e32 v135, 0xffff0000, v127
	ds_write_b128 v49, v[128:131]
	ds_write_b128 v49, v[132:135] offset:16
	s_mov_b64 exec, vcc
	s_waitcnt vmcnt(3)
	ds_write_b128 v27, v[104:107]
	v_add_u32_e32 v27, 0x2100, v27
	s_waitcnt vmcnt(2)
	ds_write_b128 v27, v[108:111]
	v_add_u32_e32 v27, 0x2100, v27
	s_waitcnt vmcnt(1)
	ds_write_b128 v27, v[112:115]
	v_add_u32_e32 v27, 0x2100, v27
	s_waitcnt vmcnt(0)
	ds_write_b128 v27, v[116:119]
	v_add_u32_e32 v27, 0x2100, v27
	s_or_b64 exec, exec, s[14:15]
	v_or_b32_e32 v10, s33, v29
	v_readlane_b32 s36, v249, 0
	v_lshlrev_b32_e32 v10, 2, v10
	v_readlane_b32 s48, v249, 12
	v_readlane_b32 s49, v249, 13
	s_waitcnt lgkmcnt(0)
	s_barrier
	v_lshl_add_u64 v[108:109], s[48:49], 0, v[10:11]
	v_add_co_u32_e32 v26, vcc, 0x8000, v108
	s_nop 1
	v_addc_co_u32_e32 v27, vcc, 0, v109, vcc
	v_add_co_u32_e32 v100, vcc, s22, v108
	v_readlane_b32 s50, v249, 14
	s_nop 0
	v_addc_co_u32_e32 v101, vcc, 0, v109, vcc
	v_add_co_u32_e32 v102, vcc, 0xa000, v108
	v_readlane_b32 s51, v249, 15
	s_nop 0
	v_addc_co_u32_e32 v103, vcc, 0, v109, vcc
	v_add_co_u32_e32 v104, vcc, 0xb000, v108
	v_readlane_b32 s37, v249, 1
	s_nop 0
	v_addc_co_u32_e32 v105, vcc, 0, v109, vcc
	global_load_dword v98, v[26:27], off
	global_load_dword v97, v[26:27], off offset:2048
	global_load_dword v95, v[100:101], off
	global_load_dword v94, v[100:101], off offset:2048
	s_nop 0
	global_load_dword v26, v[102:103], off
	global_load_dword v23, v[102:103], off offset:2048
	global_load_dword v27, v[104:105], off
	global_load_dword v25, v[104:105], off offset:2048
	global_load_dword v96, v10, s[50:51] offset:2048
	v_add_co_u32_e32 v100, vcc, s24, v108
	v_mov_b32_e32 v10, 0
	s_nop 0
	v_addc_co_u32_e32 v101, vcc, 0, v109, vcc
	v_add_co_u32_e32 v110, vcc, 0xd000, v108
	v_readlane_b32 s38, v249, 2
	s_nop 0
	v_addc_co_u32_e32 v111, vcc, 0, v109, vcc
	v_add_co_u32_e32 v112, vcc, 0xe000, v108
	v_readlane_b32 s39, v249, 3
	s_nop 0
	v_addc_co_u32_e32 v113, vcc, 0, v109, vcc
	global_load_dword v106, v[100:101], off
	global_load_dword v105, v[100:101], off offset:2048
	global_load_dword v103, v[110:111], off
	s_nop 0
	global_load_dword v101, v[110:111], off offset:2048
	global_load_dword v99, v[112:113], off
	v_add_co_u32_e32 v108, vcc, 0xf000, v108
	v_readlane_b32 s40, v249, 4
	s_nop 0
	v_addc_co_u32_e32 v109, vcc, 0, v109, vcc
	global_load_dword v104, v[112:113], off offset:2048
	global_load_dword v102, v[108:109], off
	global_load_dword v100, v[108:109], off offset:2048
	ds_read_b128 v[108:111], v54
	ds_read_b128 v[112:115], v54 offset:16
	ds_read_b128 v[116:119], v54 offset:32
	ds_read_b128 v[120:123], v54 offset:48
	ds_read_b128 v[124:127], v55
	ds_read_b128 v[128:131], v55 offset:16
	ds_read_b128 v[132:135], v55 offset:32
	ds_read_b128 v[136:139], v55 offset:48
	v_readlane_b32 s41, v249, 5
	v_readlane_b32 s42, v249, 6
	v_readlane_b32 s43, v249, 7
	v_readlane_b32 s44, v249, 8
	v_readlane_b32 s45, v249, 9
	v_readlane_b32 s46, v249, 10
	v_readlane_b32 s47, v249, 11
	s_waitcnt vmcnt(8) lgkmcnt(7)
	v_fma_f32 v107, v98, v108, v96
	v_fmac_f32_e32 v107, v97, v109
	v_fmac_f32_e32 v107, v95, v110
	v_fmac_f32_e32 v107, v94, v111
	s_waitcnt lgkmcnt(6)
	v_fmac_f32_e32 v107, v26, v112
	s_waitcnt lgkmcnt(3)
	v_fma_f32 v124, v98, v124, v96
	v_fmac_f32_e32 v107, v23, v113
	v_fmac_f32_e32 v124, v97, v125
	v_fmac_f32_e32 v107, v27, v114
	v_fmac_f32_e32 v124, v95, v126
	v_fmac_f32_e32 v107, v25, v115
	v_fmac_f32_e32 v124, v94, v127
	s_waitcnt vmcnt(7)
	v_fmac_f32_e32 v107, v106, v116
	s_waitcnt lgkmcnt(2)
	v_fmac_f32_e32 v124, v26, v128
	s_waitcnt vmcnt(6)
	v_fmac_f32_e32 v107, v105, v117
	v_fmac_f32_e32 v124, v23, v129
	s_waitcnt vmcnt(5)
	v_fmac_f32_e32 v107, v103, v118
	v_fmac_f32_e32 v124, v27, v130
	s_waitcnt vmcnt(4)
	v_fmac_f32_e32 v107, v101, v119
	v_fmac_f32_e32 v124, v25, v131
	s_waitcnt vmcnt(3)
	v_fmac_f32_e32 v107, v99, v120
	s_waitcnt lgkmcnt(1)
	v_fmac_f32_e32 v124, v106, v132
	s_waitcnt vmcnt(2)
	v_fmac_f32_e32 v107, v104, v121
	v_fmac_f32_e32 v124, v105, v133
	s_waitcnt vmcnt(1)
	v_fmac_f32_e32 v107, v102, v122
	v_fmac_f32_e32 v124, v103, v134
	s_waitcnt vmcnt(0)
	v_fmac_f32_e32 v107, v100, v123
	v_fmac_f32_e32 v124, v101, v135
	v_mul_f32_e64 v108, |v107|, s27
	s_waitcnt lgkmcnt(0)
	v_fmac_f32_e32 v124, v99, v136
	v_exp_f32_e32 v108, v108
	v_fmac_f32_e32 v124, v104, v137
	v_fmac_f32_e32 v124, v102, v138
	v_fmac_f32_e32 v124, v100, v139
	v_add_f32_e32 v108, 1.0, v108
	v_mul_f32_e64 v109, |v124|, s27
	v_log_f32_e32 v108, v108
	v_exp_f32_e32 v109, v109
	v_min_f32_e32 v107, 0, v107
	v_fmac_f32_e32 v107, 0xbf317218, v108
	v_add_f32_e32 v112, 1.0, v109
	ds_read_b128 v[108:111], v56
	v_fma_f32 v107, v107, s28, 0
	ds_write_b32 v77, v107 offset:4096
	v_log_f32_e32 v125, v112
	ds_read_b128 v[112:115], v56 offset:16
	ds_read_b128 v[116:119], v56 offset:32
	ds_read_b128 v[120:123], v56 offset:48
	s_waitcnt lgkmcnt(4)
	v_fma_f32 v108, v98, v108, v96
	v_fmac_f32_e32 v108, v97, v109
	v_fmac_f32_e32 v108, v95, v110
	v_fmac_f32_e32 v108, v94, v111
	s_waitcnt lgkmcnt(2)
	v_fmac_f32_e32 v108, v26, v112
	v_fmac_f32_e32 v108, v23, v113
	v_fmac_f32_e32 v108, v27, v114
	v_fmac_f32_e32 v108, v25, v115
	s_waitcnt lgkmcnt(1)
	v_fmac_f32_e32 v108, v106, v116
	v_fmac_f32_e32 v108, v105, v117
	v_fmac_f32_e32 v108, v103, v118
	v_fmac_f32_e32 v108, v101, v119
	s_waitcnt lgkmcnt(0)
	v_fmac_f32_e32 v108, v99, v120
	v_fmac_f32_e32 v108, v104, v121
	v_fmac_f32_e32 v108, v102, v122
	v_fmac_f32_e32 v108, v100, v123
	v_mul_f32_e64 v109, |v108|, s27
	v_exp_f32_e32 v109, v109
	v_min_f32_e32 v110, 0, v124
	v_fmac_f32_e32 v110, 0xbf317218, v125
	v_fmac_f32_e32 v107, 0x3d800000, v110
	v_add_f32_e32 v109, 1.0, v109
	v_log_f32_e32 v112, v109
	v_min_f32_e32 v124, 0, v108
	ds_read_b128 v[108:111], v57
	ds_write_b32 v78, v107 offset:4096
	v_fmac_f32_e32 v124, 0xbf317218, v112
	ds_read_b128 v[112:115], v57 offset:16
	ds_read_b128 v[116:119], v57 offset:32
	ds_read_b128 v[120:123], v57 offset:48
	v_fmac_f32_e32 v107, 0x3d800000, v124
	s_waitcnt lgkmcnt(4)
	v_fma_f32 v108, v98, v108, v96
	v_fmac_f32_e32 v108, v97, v109
	v_fmac_f32_e32 v108, v95, v110
	v_fmac_f32_e32 v108, v94, v111
	s_waitcnt lgkmcnt(2)
	v_fmac_f32_e32 v108, v26, v112
	v_fmac_f32_e32 v108, v23, v113
	v_fmac_f32_e32 v108, v27, v114
	v_fmac_f32_e32 v108, v25, v115
	s_waitcnt lgkmcnt(1)
	v_fmac_f32_e32 v108, v106, v116
	v_fmac_f32_e32 v108, v105, v117
	v_fmac_f32_e32 v108, v103, v118
	v_fmac_f32_e32 v108, v101, v119
	s_waitcnt lgkmcnt(0)
	v_fmac_f32_e32 v108, v99, v120
	v_fmac_f32_e32 v108, v104, v121
	v_fmac_f32_e32 v108, v102, v122
	v_fmac_f32_e32 v108, v100, v123
	v_mul_f32_e64 v109, |v108|, s27
	v_exp_f32_e32 v109, v109
	v_min_f32_e32 v124, 0, v108
	ds_write_b32 v79, v107 offset:4096
	v_add_f32_e32 v112, 1.0, v109
	ds_read_b128 v[108:111], v58
	v_log_f32_e32 v125, v112
	ds_read_b128 v[112:115], v58 offset:16
	ds_read_b128 v[116:119], v58 offset:32
	ds_read_b128 v[120:123], v58 offset:48
	s_waitcnt lgkmcnt(3)
	v_fma_f32 v126, v98, v108, v96
	v_fmac_f32_e32 v126, v97, v109
	v_fmac_f32_e32 v126, v95, v110
	v_fmac_f32_e32 v126, v94, v111
	s_waitcnt lgkmcnt(2)
	v_fmac_f32_e32 v126, v26, v112
	v_fmac_f32_e32 v126, v23, v113
	v_fmac_f32_e32 v126, v27, v114
	v_fmac_f32_e32 v126, v25, v115
	s_waitcnt lgkmcnt(1)
	v_fmac_f32_e32 v126, v106, v116
	v_fmac_f32_e32 v126, v105, v117
	v_fmac_f32_e32 v126, v103, v118
	v_fmac_f32_e32 v126, v101, v119
	s_waitcnt lgkmcnt(0)
	v_fmac_f32_e32 v126, v99, v120
	v_fmac_f32_e32 v126, v104, v121
	v_fmac_f32_e32 v126, v102, v122
	v_fmac_f32_e32 v126, v100, v123
	v_mul_f32_e64 v108, |v126|, s27
	v_exp_f32_e32 v108, v108
	v_fmac_f32_e32 v124, 0xbf317218, v125
	v_fmac_f32_e32 v107, 0x3d800000, v124
	ds_write_b32 v80, v107 offset:4096
	v_add_f32_e32 v112, 1.0, v108
	ds_read_b128 v[108:111], v59
	v_log_f32_e32 v124, v112
	ds_read_b128 v[112:115], v59 offset:16
	ds_read_b128 v[116:119], v59 offset:32
	ds_read_b128 v[120:123], v59 offset:48
	s_waitcnt lgkmcnt(3)
	v_fma_f32 v108, v98, v108, v96
	v_fmac_f32_e32 v108, v97, v109
	v_fmac_f32_e32 v108, v95, v110
	v_fmac_f32_e32 v108, v94, v111
	s_waitcnt lgkmcnt(2)
	v_fmac_f32_e32 v108, v26, v112
	v_fmac_f32_e32 v108, v23, v113
	v_fmac_f32_e32 v108, v27, v114
	v_fmac_f32_e32 v108, v25, v115
	s_waitcnt lgkmcnt(1)
	v_fmac_f32_e32 v108, v106, v116
	v_fmac_f32_e32 v108, v105, v117
	v_fmac_f32_e32 v108, v103, v118
	v_fmac_f32_e32 v108, v101, v119
	s_waitcnt lgkmcnt(0)
	v_fmac_f32_e32 v108, v99, v120
	v_fmac_f32_e32 v108, v104, v121
	v_fmac_f32_e32 v108, v102, v122
	v_fmac_f32_e32 v108, v100, v123
	v_mul_f32_e64 v109, |v108|, s27
	v_exp_f32_e32 v109, v109
	v_min_f32_e32 v110, 0, v126
	v_fmac_f32_e32 v110, 0xbf317218, v124
	v_fmac_f32_e32 v107, 0x3d800000, v110
	v_add_f32_e32 v109, 1.0, v109
	v_log_f32_e32 v112, v109
	v_min_f32_e32 v124, 0, v108
	ds_read_b128 v[108:111], v60
	ds_write_b32 v81, v107 offset:4096
	v_fmac_f32_e32 v124, 0xbf317218, v112
	ds_read_b128 v[112:115], v60 offset:16
	ds_read_b128 v[116:119], v60 offset:32
	ds_read_b128 v[120:123], v60 offset:48
	v_fmac_f32_e32 v107, 0x3d800000, v124
	s_waitcnt lgkmcnt(4)
	v_fma_f32 v108, v98, v108, v96
	v_fmac_f32_e32 v108, v97, v109
	v_fmac_f32_e32 v108, v95, v110
	v_fmac_f32_e32 v108, v94, v111
	s_waitcnt lgkmcnt(2)
	v_fmac_f32_e32 v108, v26, v112
	v_fmac_f32_e32 v108, v23, v113
	v_fmac_f32_e32 v108, v27, v114
	v_fmac_f32_e32 v108, v25, v115
	s_waitcnt lgkmcnt(1)
	v_fmac_f32_e32 v108, v106, v116
	v_fmac_f32_e32 v108, v105, v117
	v_fmac_f32_e32 v108, v103, v118
	v_fmac_f32_e32 v108, v101, v119
	s_waitcnt lgkmcnt(0)
	v_fmac_f32_e32 v108, v99, v120
	v_fmac_f32_e32 v108, v104, v121
	v_fmac_f32_e32 v108, v102, v122
	v_fmac_f32_e32 v108, v100, v123
	v_mul_f32_e64 v109, |v108|, s27
	v_exp_f32_e32 v109, v109
	v_min_f32_e32 v124, 0, v108
	ds_write_b32 v82, v107 offset:4096
	v_add_f32_e32 v112, 1.0, v109
	ds_read_b128 v[108:111], v61
	v_log_f32_e32 v125, v112
	ds_read_b128 v[112:115], v61 offset:16
	ds_read_b128 v[116:119], v61 offset:32
	ds_read_b128 v[120:123], v61 offset:48
	s_waitcnt lgkmcnt(3)
	v_fma_f32 v126, v98, v108, v96
	v_fmac_f32_e32 v126, v97, v109
	v_fmac_f32_e32 v126, v95, v110
	v_fmac_f32_e32 v126, v94, v111
	s_waitcnt lgkmcnt(2)
	v_fmac_f32_e32 v126, v26, v112
	v_fmac_f32_e32 v126, v23, v113
	v_fmac_f32_e32 v126, v27, v114
	v_fmac_f32_e32 v126, v25, v115
	s_waitcnt lgkmcnt(1)
	v_fmac_f32_e32 v126, v106, v116
	v_fmac_f32_e32 v126, v105, v117
	v_fmac_f32_e32 v126, v103, v118
	v_fmac_f32_e32 v126, v101, v119
	s_waitcnt lgkmcnt(0)
	v_fmac_f32_e32 v126, v99, v120
	v_fmac_f32_e32 v126, v104, v121
	v_fmac_f32_e32 v126, v102, v122
	v_fmac_f32_e32 v126, v100, v123
	v_mul_f32_e64 v108, |v126|, s27
	v_exp_f32_e32 v108, v108
	v_fmac_f32_e32 v124, 0xbf317218, v125
	v_fmac_f32_e32 v107, 0x3d800000, v124
	ds_write_b32 v83, v107 offset:4096
	v_add_f32_e32 v112, 1.0, v108
	ds_read_b128 v[108:111], v62
	v_log_f32_e32 v124, v112
	ds_read_b128 v[112:115], v62 offset:16
	ds_read_b128 v[116:119], v62 offset:32
	ds_read_b128 v[120:123], v62 offset:48
	s_waitcnt lgkmcnt(3)
	v_fma_f32 v108, v98, v108, v96
	v_fmac_f32_e32 v108, v97, v109
	v_fmac_f32_e32 v108, v95, v110
	v_fmac_f32_e32 v108, v94, v111
	s_waitcnt lgkmcnt(2)
	v_fmac_f32_e32 v108, v26, v112
	v_fmac_f32_e32 v108, v23, v113
	v_fmac_f32_e32 v108, v27, v114
	v_fmac_f32_e32 v108, v25, v115
	s_waitcnt lgkmcnt(1)
	v_fmac_f32_e32 v108, v106, v116
	v_fmac_f32_e32 v108, v105, v117
	v_fmac_f32_e32 v108, v103, v118
	v_fmac_f32_e32 v108, v101, v119
	s_waitcnt lgkmcnt(0)
	v_fmac_f32_e32 v108, v99, v120
	v_fmac_f32_e32 v108, v104, v121
	v_fmac_f32_e32 v108, v102, v122
	v_fmac_f32_e32 v108, v100, v123
	v_mul_f32_e64 v109, |v108|, s27
	v_exp_f32_e32 v109, v109
	v_min_f32_e32 v110, 0, v126
	v_fmac_f32_e32 v110, 0xbf317218, v124
	v_fmac_f32_e32 v107, 0x3d800000, v110
	v_add_f32_e32 v109, 1.0, v109
	v_log_f32_e32 v112, v109
	v_min_f32_e32 v124, 0, v108
	ds_read_b128 v[108:111], v63
	ds_write_b32 v84, v107 offset:4096
	v_fmac_f32_e32 v124, 0xbf317218, v112
	ds_read_b128 v[112:115], v63 offset:16
	ds_read_b128 v[116:119], v63 offset:32
	ds_read_b128 v[120:123], v63 offset:48
	v_fmac_f32_e32 v107, 0x3d800000, v124
	s_waitcnt lgkmcnt(4)
	v_fma_f32 v108, v98, v108, v96
	v_fmac_f32_e32 v108, v97, v109
	v_fmac_f32_e32 v108, v95, v110
	v_fmac_f32_e32 v108, v94, v111
	s_waitcnt lgkmcnt(2)
	v_fmac_f32_e32 v108, v26, v112
	v_fmac_f32_e32 v108, v23, v113
	v_fmac_f32_e32 v108, v27, v114
	v_fmac_f32_e32 v108, v25, v115
	s_waitcnt lgkmcnt(1)
	v_fmac_f32_e32 v108, v106, v116
	v_fmac_f32_e32 v108, v105, v117
	v_fmac_f32_e32 v108, v103, v118
	v_fmac_f32_e32 v108, v101, v119
	s_waitcnt lgkmcnt(0)
	v_fmac_f32_e32 v108, v99, v120
	v_fmac_f32_e32 v108, v104, v121
	v_fmac_f32_e32 v108, v102, v122
	v_fmac_f32_e32 v108, v100, v123
	v_mul_f32_e64 v109, |v108|, s27
	v_exp_f32_e32 v109, v109
	v_min_f32_e32 v124, 0, v108
	ds_write_b32 v85, v107 offset:4096
	v_add_f32_e32 v112, 1.0, v109
	ds_read_b128 v[108:111], v64
	v_log_f32_e32 v125, v112
	ds_read_b128 v[112:115], v64 offset:16
	ds_read_b128 v[116:119], v64 offset:32
	ds_read_b128 v[120:123], v64 offset:48
	s_waitcnt lgkmcnt(3)
	v_fma_f32 v126, v98, v108, v96
	v_fmac_f32_e32 v126, v97, v109
	v_fmac_f32_e32 v126, v95, v110
	v_fmac_f32_e32 v126, v94, v111
	s_waitcnt lgkmcnt(2)
	v_fmac_f32_e32 v126, v26, v112
	v_fmac_f32_e32 v126, v23, v113
	v_fmac_f32_e32 v126, v27, v114
	v_fmac_f32_e32 v126, v25, v115
	s_waitcnt lgkmcnt(1)
	v_fmac_f32_e32 v126, v106, v116
	v_fmac_f32_e32 v126, v105, v117
	v_fmac_f32_e32 v126, v103, v118
	v_fmac_f32_e32 v126, v101, v119
	s_waitcnt lgkmcnt(0)
	v_fmac_f32_e32 v126, v99, v120
	v_fmac_f32_e32 v126, v104, v121
	v_fmac_f32_e32 v126, v102, v122
	v_fmac_f32_e32 v126, v100, v123
	v_mul_f32_e64 v108, |v126|, s27
	v_exp_f32_e32 v108, v108
	v_fmac_f32_e32 v124, 0xbf317218, v125
	v_fmac_f32_e32 v107, 0x3d800000, v124
	ds_write_b32 v86, v107 offset:4096
	v_add_f32_e32 v112, 1.0, v108
	ds_read_b128 v[108:111], v65
	v_log_f32_e32 v124, v112
	ds_read_b128 v[112:115], v65 offset:16
	ds_read_b128 v[116:119], v65 offset:32
	ds_read_b128 v[120:123], v65 offset:48
	s_waitcnt lgkmcnt(3)
	v_fma_f32 v108, v98, v108, v96
	v_fmac_f32_e32 v108, v97, v109
	v_fmac_f32_e32 v108, v95, v110
	v_fmac_f32_e32 v108, v94, v111
	s_waitcnt lgkmcnt(2)
	v_fmac_f32_e32 v108, v26, v112
	v_fmac_f32_e32 v108, v23, v113
	v_fmac_f32_e32 v108, v27, v114
	v_fmac_f32_e32 v108, v25, v115
	s_waitcnt lgkmcnt(1)
	v_fmac_f32_e32 v108, v106, v116
	v_fmac_f32_e32 v108, v105, v117
	v_fmac_f32_e32 v108, v103, v118
	v_fmac_f32_e32 v108, v101, v119
	s_waitcnt lgkmcnt(0)
	v_fmac_f32_e32 v108, v99, v120
	v_fmac_f32_e32 v108, v104, v121
	v_fmac_f32_e32 v108, v102, v122
	v_fmac_f32_e32 v108, v100, v123
	v_mul_f32_e64 v109, |v108|, s27
	v_exp_f32_e32 v109, v109
	v_min_f32_e32 v110, 0, v126
	v_fmac_f32_e32 v110, 0xbf317218, v124
	v_fmac_f32_e32 v107, 0x3d800000, v110
	v_add_f32_e32 v109, 1.0, v109
	v_log_f32_e32 v112, v109
	v_min_f32_e32 v124, 0, v108
	ds_read_b128 v[108:111], v66
	ds_write_b32 v87, v107 offset:4096
	v_fmac_f32_e32 v124, 0xbf317218, v112
	ds_read_b128 v[112:115], v66 offset:16
	ds_read_b128 v[116:119], v66 offset:32
	ds_read_b128 v[120:123], v66 offset:48
	v_fmac_f32_e32 v107, 0x3d800000, v124
	s_waitcnt lgkmcnt(4)
	v_fma_f32 v108, v98, v108, v96
	v_fmac_f32_e32 v108, v97, v109
	v_fmac_f32_e32 v108, v95, v110
	v_fmac_f32_e32 v108, v94, v111
	s_waitcnt lgkmcnt(2)
	v_fmac_f32_e32 v108, v26, v112
	v_fmac_f32_e32 v108, v23, v113
	v_fmac_f32_e32 v108, v27, v114
	v_fmac_f32_e32 v108, v25, v115
	s_waitcnt lgkmcnt(1)
	v_fmac_f32_e32 v108, v106, v116
	v_fmac_f32_e32 v108, v105, v117
	v_fmac_f32_e32 v108, v103, v118
	v_fmac_f32_e32 v108, v101, v119
	s_waitcnt lgkmcnt(0)
	v_fmac_f32_e32 v108, v99, v120
	v_fmac_f32_e32 v108, v104, v121
	v_fmac_f32_e32 v108, v102, v122
	v_fmac_f32_e32 v108, v100, v123
	v_mul_f32_e64 v109, |v108|, s27
	v_exp_f32_e32 v109, v109
	v_min_f32_e32 v124, 0, v108
	ds_write_b32 v88, v107 offset:4096
	v_add_f32_e32 v112, 1.0, v109
	ds_read_b128 v[108:111], v67
	v_log_f32_e32 v125, v112
	ds_read_b128 v[112:115], v67 offset:16
	ds_read_b128 v[116:119], v67 offset:32
	ds_read_b128 v[120:123], v67 offset:48
	s_waitcnt lgkmcnt(3)
	v_fma_f32 v126, v98, v108, v96
	v_fmac_f32_e32 v126, v97, v109
	v_fmac_f32_e32 v126, v95, v110
	v_fmac_f32_e32 v126, v94, v111
	s_waitcnt lgkmcnt(2)
	v_fmac_f32_e32 v126, v26, v112
	v_fmac_f32_e32 v126, v23, v113
	v_fmac_f32_e32 v126, v27, v114
	v_fmac_f32_e32 v126, v25, v115
	s_waitcnt lgkmcnt(1)
	v_fmac_f32_e32 v126, v106, v116
	v_fmac_f32_e32 v126, v105, v117
	v_fmac_f32_e32 v126, v103, v118
	v_fmac_f32_e32 v126, v101, v119
	s_waitcnt lgkmcnt(0)
	v_fmac_f32_e32 v126, v99, v120
	v_fmac_f32_e32 v126, v104, v121
	v_fmac_f32_e32 v126, v102, v122
	v_fmac_f32_e32 v126, v100, v123
	v_mul_f32_e64 v108, |v126|, s27
	v_exp_f32_e32 v108, v108
	v_fmac_f32_e32 v124, 0xbf317218, v125
	v_fmac_f32_e32 v107, 0x3d800000, v124
	ds_write_b32 v89, v107 offset:4096
	v_add_f32_e32 v112, 1.0, v108
	ds_read_b128 v[108:111], v68
	v_log_f32_e32 v124, v112
	ds_read_b128 v[112:115], v68 offset:16
	ds_read_b128 v[116:119], v68 offset:32
	ds_read_b128 v[120:123], v68 offset:48
	s_waitcnt lgkmcnt(3)
	v_fma_f32 v125, v98, v108, v96
	v_fmac_f32_e32 v125, v97, v109
	v_fmac_f32_e32 v125, v95, v110
	v_fmac_f32_e32 v125, v94, v111
	s_waitcnt lgkmcnt(2)
	v_fmac_f32_e32 v125, v26, v112
	v_fmac_f32_e32 v125, v23, v113
	v_fmac_f32_e32 v125, v27, v114
	v_fmac_f32_e32 v125, v25, v115
	s_waitcnt lgkmcnt(1)
	v_fmac_f32_e32 v125, v106, v116
	v_fmac_f32_e32 v125, v105, v117
	v_fmac_f32_e32 v125, v103, v118
	v_fmac_f32_e32 v125, v101, v119
	s_waitcnt lgkmcnt(0)
	v_fmac_f32_e32 v125, v99, v120
	v_fmac_f32_e32 v125, v104, v121
	v_fmac_f32_e32 v125, v102, v122
	v_fmac_f32_e32 v125, v100, v123
	v_mul_f32_e64 v108, |v125|, s27
	v_exp_f32_e32 v108, v108
	v_min_f32_e32 v109, 0, v126
	v_fmac_f32_e32 v109, 0xbf317218, v124
	v_fmac_f32_e32 v107, 0x3d800000, v109
	v_add_f32_e32 v112, 1.0, v108
	ds_read_b128 v[108:111], v69
	v_log_f32_e32 v124, v112
	ds_read_b128 v[112:115], v69 offset:16
	ds_read_b128 v[116:119], v69 offset:32
	ds_read_b128 v[120:123], v69 offset:48
	ds_write_b32 v90, v107 offset:4096
	s_waitcnt lgkmcnt(4)
	v_fmac_f32_e32 v96, v98, v108
	v_fmac_f32_e32 v96, v97, v109
	v_fmac_f32_e32 v96, v95, v110
	v_fmac_f32_e32 v96, v94, v111
	s_waitcnt lgkmcnt(3)
	v_fmac_f32_e32 v96, v26, v112
	v_fmac_f32_e32 v96, v23, v113
	v_fmac_f32_e32 v96, v27, v114
	v_fmac_f32_e32 v96, v25, v115
	s_waitcnt lgkmcnt(2)
	v_fmac_f32_e32 v96, v106, v116
	v_fmac_f32_e32 v96, v105, v117
	v_fmac_f32_e32 v96, v103, v118
	v_fmac_f32_e32 v96, v101, v119
	s_waitcnt lgkmcnt(1)
	v_fmac_f32_e32 v96, v99, v120
	v_fmac_f32_e32 v96, v104, v121
	v_fmac_f32_e32 v96, v102, v122
	v_fmac_f32_e32 v96, v100, v123
	v_mul_f32_e64 v23, |v96|, s27
	v_exp_f32_e32 v23, v23
	v_min_f32_e32 v25, 0, v125
	v_fmac_f32_e32 v25, 0xbf317218, v124
	v_fmac_f32_e32 v107, 0x3d800000, v25
	v_add_f32_e32 v23, 1.0, v23
	v_log_f32_e32 v23, v23
	v_min_f32_e32 v25, 0, v96
	ds_write_b32 v91, v107 offset:4096
	v_fmac_f32_e32 v25, 0xbf317218, v23
	v_fmac_f32_e32 v107, 0x3d800000, v25
	ds_write_b32 v92, v107 offset:4096
	ds_write_b32 v192, v107 offset:36864
	s_waitcnt lgkmcnt(0)
	s_barrier
	s_and_saveexec_b64 s[14:15], s[6:7]
	s_cbranch_execz .LBB0_1245
	v_mov_b32_e32 v10, 0
	s_mov_b64 s[16:17], 0
	v_mov_b32_e32 v23, v53
	v_mov_b32_e32 v25, v196
